# adds: row_post loads hoisted to row start with counted vmcnt; ret_kv second load pair hoisted; ret_scan rewritten with two 16-chunk load batches in flight
# speedup vs baseline: 1.0194x; 1.0053x over previous
; __device__ __forceinline__ float bf2f(unsigned b) { return __uint_as_float(b << 16); }
; __device__ __forceinline__ bf16 f2bf(float f) { return (bf16)(pk2(f, 0.f) & 0xffffu); }
; __device__ __forceinline__ float ex2f(float x) { return __builtin_amdgcn_exp2f(x); }
; __device__ __forceinline__ void row_post(bf16* Z, bf16* CQN, bf16* CKV, bf16* KR, float* out, const float* qg, const float* kvg, int r, int lane) {
;     ...
;     { const float inv = ex2f(-(float)lane * (1.0f / 63.0f) * LG2_10000); float s, c; sincos_rev(pos * inv, s, c);
; #pragma unroll
;       for (int hh = 0; hh < 4; ++hh) {
;           bf16* q = z + ZC_RQ + hh * 128; const float a1 = bf2f(q[lane]), a2 = bf2f(q[64 + lane]); q[lane] = f2bf(a1 * c - a2 * s); q[64 + lane] = f2bf(a2 * c + a1 * s);
;           bf16* k = z + ZC_RK + hh * 128; const float b1 = bf2f(k[lane]), b2 = bf2f(k[64 + lane]); const float ks = 0.08838834764831845f;
;           k[lane] = f2bf((b1 * c - b2 * s) * ks); k[64 + lane] = f2bf((b2 * c + b1 * s) * ks); } }
.LBB0_320:
	s_or_b64 exec, exec, s[18:19]
	v_add_co_u32_e32 v32, vcc, 0x6800000, v32
	v_mul_f32_e32 v41, v36, v41
	s_nop 0
	v_addc_co_u32_e32 v33, vcc, 0, v33, vcc
	v_mul_f32_e32 v56, 0.15915494, v41
	v_floor_f32_e32 v56, v56
	v_fma_f32 v41, v41, 0.15915494, -v56
	v_sin_f32_e32 v56, v41
	v_cos_f32_e32 v41, v41
	s_add_u32 s14, s14, 0x1400
	s_addc_u32 s15, s15, 0
	s_add_u32 s12, s12, 1
	s_addc_u32 s13, s13, 0
	s_add_u32 s10, s10, 0x200
	s_addc_u32 s11, s11, 0
	v_lshl_add_u64 v[20:21], v[20:21], 0, s[6:7]
	s_cmpk_eq_u32 s14, 0xa000
	v_lshl_add_u64 v[22:23], v[22:23], 0, 64
	s_waitcnt vmcnt(2) lgkmcnt(0)
	v_mov_b32_e32 v42, v76
	v_mov_b32_e32 v43, v77
	v_mov_b32_e32 v44, v78
	v_mov_b32_e32 v45, v79
	v_mov_b32_e32 v46, v80
	v_mov_b32_e32 v47, v81
	v_mov_b32_e32 v48, v82
	v_mov_b32_e32 v49, v83
	v_mov_b32_e32 v50, v84
	v_mov_b32_e32 v51, v85
	v_mov_b32_e32 v52, v86
	v_mov_b32_e32 v53, v87
	v_mov_b32_e32 v54, v88
	v_mov_b32_e32 v55, v89
	v_mov_b32_e32 v57, v90
	v_mov_b32_e32 v58, v91
	v_lshlrev_b32_e32 v42, 16, v42
	v_lshlrev_b32_e32 v43, 16, v43
	v_lshlrev_b32_e32 v44, 16, v44
	v_lshlrev_b32_e32 v45, 16, v45
	v_mul_f32_e32 v59, v56, v43
	v_lshlrev_b32_e32 v47, 16, v47
	v_mul_f32_e32 v43, v41, v43
	v_lshlrev_b32_e32 v49, 16, v49
	v_mul_f32_e32 v60, v56, v45
	v_lshlrev_b32_e32 v51, 16, v51
	v_lshlrev_b32_e32 v46, 16, v46
	v_lshlrev_b32_e32 v53, 16, v53
	v_lshlrev_b32_e32 v48, 16, v48
	v_lshlrev_b32_e32 v50, 16, v50
	v_lshlrev_b32_e32 v52, 16, v52
	v_mul_f32_e32 v45, v41, v45
	v_mul_f32_e32 v61, v56, v47
	v_mul_f32_e32 v47, v41, v47
	v_mul_f32_e32 v62, v56, v49
	v_mul_f32_e32 v49, v41, v49
	v_mul_f32_e32 v63, v56, v51
	v_mul_f32_e32 v51, v41, v51
	v_mul_f32_e32 v64, v56, v53
	v_fma_f32 v59, v41, v42, -v59
	v_fmac_f32_e32 v43, v56, v42
	v_fma_f32 v42, v41, v44, -v60
	v_fmac_f32_e32 v45, v56, v44
	v_fma_f32 v44, v41, v46, -v61
	v_fmac_f32_e32 v47, v56, v46
	v_fma_f32 v46, v41, v48, -v62
	v_fmac_f32_e32 v49, v56, v48
	v_fma_f32 v48, v41, v50, -v63
	v_fmac_f32_e32 v51, v56, v50
	v_fma_f32 v50, v41, v52, -v64
	v_mul_f32_e32 v42, 0x3db504f3, v42
	v_cvt_pk_bf16_f32 v59, v59, s0
	v_cvt_pk_bf16_f32 v43, v43, s0
	v_mul_f32_e32 v45, 0x3db504f3, v45
	v_cvt_pk_bf16_f32 v44, v44, s0
	v_mul_f32_e32 v46, 0x3db504f3, v46
	v_mul_f32_e32 v49, 0x3db504f3, v49
	v_cvt_pk_bf16_f32 v48, v48, s0
	v_mul_f32_e32 v50, 0x3db504f3, v50
	v_cvt_pk_bf16_f32 v42, v42, s0
	v_cvt_pk_bf16_f32 v47, v47, s0
	v_cvt_pk_bf16_f32 v51, v51, s0
	global_store_short v[32:33], v59, off offset:832
	global_store_short v[32:33], v43, off offset:960
	v_cvt_pk_bf16_f32 v43, v45, s0
	global_store_short v[32:33], v44, off offset:1088
	global_store_short v[32:33], v47, off offset:1216
	v_cvt_pk_bf16_f32 v44, v46, s0
	v_cvt_pk_bf16_f32 v45, v49, s0
	global_store_short v[32:33], v48, off offset:1344
	global_store_short v[32:33], v51, off offset:1472
	v_cvt_pk_bf16_f32 v46, v50, s0
	global_store_short v[32:33], v42, off offset:1856
	global_store_short v[32:33], v43, off offset:1984
	global_store_short v[32:33], v44, off offset:2112
	global_store_short v[32:33], v45, off offset:2240
	global_store_short v[32:33], v46, off offset:2368
	v_mul_f32_e32 v42, v41, v53
	v_fmac_f32_e32 v42, v56, v52
	v_mul_f32_e32 v42, 0x3db504f3, v42
	v_cvt_pk_bf16_f32 v42, v42, s0
	v_lshlrev_b32_e32 v43, 16, v55
	global_store_short v[32:33], v42, off offset:2496
	v_lshlrev_b32_e32 v42, 16, v54
	v_mul_f32_e32 v44, v56, v43
	v_mul_f32_e32 v43, v41, v43
	v_fma_f32 v44, v41, v42, -v44
	v_fmac_f32_e32 v43, v56, v42
	v_cvt_pk_bf16_f32 v44, v44, s0
	v_cvt_pk_bf16_f32 v42, v43, s0
	v_lshlrev_b32_e32 v43, 16, v58
	global_store_short v[32:33], v44, off offset:1600
	global_store_short v[32:33], v42, off offset:1728
	v_lshlrev_b32_e32 v42, 16, v57
	v_mul_f32_e32 v44, v56, v43
	v_fma_f32 v44, v41, v42, -v44
	v_mul_f32_e32 v41, v41, v43
	v_fmac_f32_e32 v41, v56, v42
	v_mul_f32_e32 v44, 0x3db504f3, v44
	v_mul_f32_e32 v41, 0x3db504f3, v41
	v_cvt_pk_bf16_f32 v44, v44, s0
	v_cvt_pk_bf16_f32 v41, v41, s0
	global_store_short v[32:33], v44, off offset:2624
	global_store_short v[32:33], v41, off offset:2752
	s_cbranch_scc1 .LBB0_314
; __device__ __forceinline__ float bf2f(unsigned b) { return __uint_as_float(b << 16); }
; __device__ __forceinline__ float bflo(unsigned w) { return __uint_as_float(w << 16); }
; __device__ __forceinline__ float bfhi(unsigned w) { return __uint_as_float(w & 0xffff0000u); }
; __device__ __forceinline__ unsigned pk2(float lo, float hi) { const f32x2 v = {lo, hi}; return __builtin_bit_cast(unsigned, __builtin_convertvector(v, bf16x2_t)); }
; __device__ __forceinline__ bf16 f2bf(float f) { return (bf16)(pk2(f, 0.f) & 0xffffu); }
; __device__ __forceinline__ float ex2f(float x) { return __builtin_amdgcn_exp2f(x); }
; __device__ __forceinline__ void row_post(bf16* Z, bf16* CQN, bf16* CKV, bf16* KR, float* out, const float* qg, const float* kvg, int r, int lane) {
;     bf16* z = Z + (size_t)r * NZ; const float pos = (float)row_pos(r);
;     { const u32x2 raw = *(const u32x2*)(z + 4 * lane); const float v0 = bflo(raw.x), v1 = bfhi(raw.x), v2 = bflo(raw.y), v3 = bfhi(raw.y);
;       const float rstd = rsqrtf(wave_sum((v0 * v0 + v1 * v1) + (v2 * v2 + v3 * v3)) * (1.f / 256.f) + EPS); const f32x4 g = *(const f32x4*)(qg + 4 * lane);
;       u32x2 w; w.x = pk2(v0 * rstd * g.x, v1 * rstd * g.y); w.y = pk2(v2 * rstd * g.z, v3 * rstd * g.w); *(u32x2*)(CQN + (size_t)r * 256 + 4 * lane) = w; }
;     { const unsigned raw = *(const unsigned*)(z + ZC_CKV + 2 * lane); const float v0 = bflo(raw), v1 = bfhi(raw);
;       const float rstd = rsqrtf(wave_sum(v0 * v0 + v1 * v1) * (1.f / 128.f) + EPS); const f32x2 g = *(const f32x2*)(kvg + 2 * lane);
;       const float y0 = v0 * rstd * g.x, y1 = v1 * rstd * g.y;
;       float* o = (r < MP ? out + O_PCKV + (size_t)r * 128 : out + O_SCKV + (size_t)(r - MP) * 128) + 2 * lane; *(f32x2*)o = (f32x2){y0, y1};
;       if (r < MP) *(unsigned*)(CKV + (size_t)r * 128 + 2 * lane) = pk2(y0, y1); }
;     if (lane < 16) { const float x1 = bf2f(z[ZC_KR + lane]), x2 = bf2f(z[ZC_KR + 16 + lane]); const float inv = ex2f(-(float)lane * (2.0f / 32.0f) * LG2_10000);
;       float s, c; sincos_rev(pos * inv, s, c); const float o1 = x1 * c - x2 * s, o2 = x2 * c + x1 * s;
;       float* o = (r < MP ? out + O_PKR + (size_t)r * 32 : out + O_SKR + (size_t)(r - MP) * 32); o[lane] = o1; o[16 + lane] = o2;
;       if (r < MP) { KR[(size_t)r * 32 + lane] = f2bf(o1); KR[(size_t)r * 32 + 16 + lane] = f2bf(o2); } }
.LBB0_321:
	v_lshl_add_u64 v[32:33], v[30:31], 0, s[14:15]
	global_load_dwordx2 v[46:47], v[32:33], off
	global_load_dwordx4 v[42:45], v[2:3], off
	v_lshl_add_u64 v[66:67], v[28:29], 0, s[14:15]
	global_load_dword v68, v[66:67], off
	global_load_dwordx2 v[70:71], v[4:5], off
	s_mov_b64 s[98:99], 0x6800000
	v_lshl_add_u64 v[72:73], v[26:27], 0, s[14:15]
	v_lshl_add_u64 v[72:73], v[72:73], 0, s[98:99]
	s_and_saveexec_b64 s[100:101], s[2:3]
	global_load_ushort v74, v[72:73], off offset:768
	global_load_ushort v75, v[72:73], off offset:800
	s_mov_b64 exec, s[100:101]
	global_load_ushort v76, v[72:73], off offset:832
	global_load_ushort v77, v[72:73], off offset:960
	global_load_ushort v78, v[72:73], off offset:1856
	global_load_ushort v79, v[72:73], off offset:1984
	global_load_ushort v80, v[72:73], off offset:1088
	global_load_ushort v81, v[72:73], off offset:1216
	global_load_ushort v82, v[72:73], off offset:2112
	global_load_ushort v83, v[72:73], off offset:2240
	global_load_ushort v84, v[72:73], off offset:1344
	global_load_ushort v85, v[72:73], off offset:1472
	global_load_ushort v86, v[72:73], off offset:2368
	global_load_ushort v87, v[72:73], off offset:2496
	global_load_ushort v88, v[72:73], off offset:1600
	global_load_ushort v89, v[72:73], off offset:1728
	global_load_ushort v90, v[72:73], off offset:2624
	global_load_ushort v91, v[72:73], off offset:2752
	s_add_i32 s35, s8, s12
	s_cmp_lt_i32 s35, 0x8000
	s_cselect_b64 s[16:17], -1, 0
	s_add_u32 s36, s28, s10
	s_addc_u32 s37, s29, s11
	s_add_u32 s38, s31, s10
	s_addc_u32 s39, s34, s11
	s_and_b64 s[18:19], s[16:17], exec
	s_cselect_b32 s18, s36, s38
	s_cselect_b32 s19, s37, s39
	s_cmpk_gt_i32 s35, 0x7fff
	s_waitcnt vmcnt(18) lgkmcnt(0)
	v_lshlrev_b32_e32 v32, 16, v47
	v_and_b32_e32 v33, 0xffff0000, v47
	v_lshlrev_b32_e32 v48, 16, v46
	v_and_b32_e32 v49, 0xffff0000, v46
	v_pk_mul_f32 v[46:47], v[32:33], v[32:33]
	v_pk_mul_f32 v[50:51], v[48:49], v[48:49]
	v_add_f32_e32 v41, v46, v47
	v_add_f32_e32 v46, v50, v51
	v_add_f32_e32 v41, v46, v41
	ds_swizzle_b32 v46, v41 offset:swizzle(SWAP,1)
	v_lshl_add_u64 v[50:51], v[28:29], 0, s[14:15]
	s_waitcnt lgkmcnt(0)
	v_add_f32_e32 v41, v41, v46
	ds_swizzle_b32 v46, v41 offset:swizzle(SWAP,2)
	s_waitcnt lgkmcnt(0)
	v_add_f32_e32 v41, v41, v46
	ds_swizzle_b32 v46, v41 offset:swizzle(SWAP,4)
	s_waitcnt lgkmcnt(0)
	v_add_f32_e32 v41, v41, v46
	ds_swizzle_b32 v46, v41 offset:swizzle(SWAP,8)
	s_waitcnt lgkmcnt(0)
	v_add_f32_e32 v41, v41, v46
	ds_swizzle_b32 v46, v41 offset:swizzle(SWAP,16)
	s_waitcnt lgkmcnt(0)
	v_add_f32_e32 v41, v41, v46
	v_mov_b32_e32 v46, v41
	s_nop 1
	v_permlane32_swap_b32_e32 v41, v46
	v_add_f32_e32 v41, v41, v46
	v_fmamk_f32 v41, v41, 0x3b800000, v39
	v_mul_f32_e32 v46, 0x4b800000, v41
	v_cmp_gt_f32_e32 vcc, s26, v41
	s_nop 1
	v_cndmask_b32_e32 v41, v41, v46, vcc
	v_rsq_f32_e32 v41, v41
	v_lshl_add_u64 v[46:47], v[24:25], 0, s[10:11]
	v_mul_f32_e32 v52, 0x45800000, v41
	v_cndmask_b32_e32 v52, v41, v52, vcc
	v_pk_mul_f32 v[48:49], v[52:53], v[48:49] op_sel_hi:[0,1]
	v_pk_mul_f32 v[32:33], v[52:53], v[32:33] op_sel_hi:[0,1]
	v_pk_mul_f32 v[42:43], v[42:43], v[48:49]
	v_pk_mul_f32 v[32:33], v[44:45], v[32:33]
	v_cvt_pk_bf16_f32 v42, v42, v43
	v_cvt_pk_bf16_f32 v43, v32, v33
	global_store_dwordx2 v[46:47], v[42:43], off
	s_waitcnt vmcnt(17) lgkmcnt(0)
	v_mov_b32_e32 v41, v68
	v_mov_b64_e32 v[32:33], v[70:71]
	v_lshlrev_b32_e32 v42, 16, v41
	v_and_b32_e32 v43, 0xffff0000, v41
	v_pk_mul_f32 v[44:45], v[42:43], v[42:43]
	s_nop 0
	v_add_f32_e32 v41, v44, v45
	ds_swizzle_b32 v44, v41 offset:swizzle(SWAP,1)
	s_waitcnt lgkmcnt(0)
	v_add_f32_e32 v41, v41, v44
	ds_swizzle_b32 v44, v41 offset:swizzle(SWAP,2)
	s_waitcnt lgkmcnt(0)
	v_add_f32_e32 v41, v41, v44
	ds_swizzle_b32 v44, v41 offset:swizzle(SWAP,4)
	s_waitcnt lgkmcnt(0)
	v_add_f32_e32 v41, v41, v44
	ds_swizzle_b32 v44, v41 offset:swizzle(SWAP,8)
	s_waitcnt lgkmcnt(0)
	v_add_f32_e32 v41, v41, v44
	ds_swizzle_b32 v44, v41 offset:swizzle(SWAP,16)
	s_waitcnt lgkmcnt(0)
	v_add_f32_e32 v41, v41, v44
	v_mov_b32_e32 v44, v41
	s_nop 1
	v_permlane32_swap_b32_e32 v41, v44
	v_add_f32_e32 v41, v41, v44
	v_fmamk_f32 v41, v41, 0x3c000000, v39
	v_mul_f32_e32 v44, 0x4b800000, v41
	v_cmp_gt_f32_e32 vcc, s26, v41
	s_nop 1
	v_cndmask_b32_e32 v41, v41, v44, vcc
	v_rsq_f32_e32 v41, v41
	s_nop 0
	v_mul_f32_e32 v44, 0x45800000, v41
	v_cndmask_b32_e32 v44, v41, v44, vcc
	v_pk_mul_f32 v[42:43], v[44:45], v[42:43] op_sel_hi:[0,1]
	v_pk_mul_f32 v[32:33], v[32:33], v[42:43]
	v_lshl_add_u64 v[42:43], s[18:19], 0, v[18:19]
	global_store_dwordx2 v[42:43], v[32:33], off
	s_cbranch_scc1 .LBB0_323
	v_cvt_pk_bf16_f32 v32, v32, v33
	global_store_dword v[20:21], v32, off
.LBB0_323:
	s_and_b64 s[18:19], s[16:17], exec
	s_cselect_b32 s18, s30, s22
	s_add_i32 s18, s18, s12
	v_cvt_f32_u32_e32 v41, s18
	v_lshl_add_u64 v[32:33], v[26:27], 0, s[14:15]
	s_and_saveexec_b64 s[18:19], s[2:3]
	s_cbranch_execz .LBB0_320
	v_add_co_u32_e32 v42, vcc, 0x6800000, v32
	s_add_u32 s35, s8, s12
	s_nop 0
	v_addc_co_u32_e32 v43, vcc, 0, v33, vcc
	v_mul_f32_e32 v42, v35, v41
	s_addc_u32 s36, s9, s13
	v_cndmask_b32_e64 v43, 0, 1, s[16:17]
	v_mul_f32_e32 v44, 0.15915494, v42
	s_add_u32 s37, s4, s12
	v_cmp_ne_u32_e32 vcc, 1, v43
	v_floor_f32_e32 v43, v44
	s_addc_u32 s38, 0, s13
	v_fma_f32 v42, v42, 0.15915494, -v43
	s_and_b64 s[16:17], s[16:17], exec
	v_sin_f32_e32 v48, v42
	v_cos_f32_e32 v43, v42
	s_cselect_b32 s16, s35, s37
	s_cselect_b32 s35, s27, 0x9ad6000
	s_cselect_b32 s17, s36, s38
	s_add_u32 s35, s1, s35
	s_addc_u32 s36, s0, 0
	s_lshl_b64 s[16:17], s[16:17], 7
	s_add_u32 s16, s35, s16
	s_addc_u32 s17, s36, s17
	s_and_b64 vcc, exec, vcc
	v_lshl_add_u64 v[44:45], s[16:17], 0, v[0:1]
	s_waitcnt vmcnt(18) lgkmcnt(0)
	v_mov_b32_e32 v46, v74
	v_mov_b32_e32 v47, v75
	v_lshlrev_b32_e32 v46, 16, v46
	v_lshlrev_b32_e32 v42, 16, v47
	v_mul_f32_e32 v47, v48, v42
	v_mul_f32_e32 v42, v43, v42
	v_fma_f32 v43, v43, v46, -v47
	v_fmac_f32_e32 v42, v48, v46
	global_store_dword v[44:45], v43, off
	global_store_dword v[44:45], v42, off offset:64
	s_cbranch_vccnz .LBB0_320
	v_cvt_pk_bf16_f32 v45, v42, s0
	v_add_co_u32_e32 v42, vcc, 0xffffffe0, v22
	v_cvt_pk_bf16_f32 v44, v43, s0
	s_nop 0
	v_addc_co_u32_e32 v43, vcc, -1, v23, vcc
	global_store_short v[42:43], v44, off
	global_store_short v[22:23], v45, off
	s_branch .LBB0_320

; __device__ __forceinline__ float bflo(unsigned w) { return __uint_as_float(w << 16); }
; __device__ __forceinline__ float bfhi(unsigned w) { return __uint_as_float(w & 0xffff0000u); }
; __device__ __forceinline__ bf16 f2bf(float f) { return (bf16)(pk2(f, 0.f) & 0xffffu); }
; __device__ __forceinline__ float ex2f(float x) { return __builtin_amdgcn_exp2f(x); }
; __device__ __forceinline__ void ret_kv_item(LAS unsigned char* lds, const bf16* Z, bf16* AT, int b, int c, int hh, float lg) {
;     ...
;     const int tid_ = my_tid(lds); const int tid = tid_, lane = tid & 63, r32 = lane & 31, hi = lane >> 5; const int wid = __builtin_amdgcn_readfirstlane(tid >> 6);
;     const int rowbase = b * SEQ + 64 * c;
; #pragma unroll
;     for (int i = 0; i < 2; ++i) { const int ci = tid + 512 * i, l = ci & 63, dc = ci >> 6; const bf16* zr = Z + (size_t)(rowbase + l) * NZ + hh * 128 + dc * 8;
;         const u32x4 kr = *(const u32x4*)(zr + ZC_RK), vr = *(const u32x4*)(zr + ZC_RV); const float dec = ex2f((float)(63 - l) * lg);
; #pragma unroll
;         for (int e = 0; e < 4; ++e) { const unsigned kw = kr[e], vw = vr[e]; const int d = 8 * dc + 2 * e;
;             KT[d * 72 + l] = f2bf(bflo(kw) * dec); KT[(d + 1) * 72 + l] = f2bf(bfhi(kw) * dec);
;             VTt[d * 72 + l] = (bf16)(vw & 0xffffu); VTt[(d + 1) * 72 + l] = (bf16)(vw >> 16); } }
;     __syncthreads();
.LBB0_440:
	s_and_b32 s12, s11, 3
	s_bfe_u32 s13, s11, 0x80002
	s_cmp_eq_u32 s12, 1
	s_cselect_b64 vcc, -1, 0
	s_cmp_lg_u32 s12, 2
	s_getreg_b32 s2, hwreg(HW_REG_HW_ID, 0, 6)
	v_cndmask_b32_e32 v0, v34, v35, vcc
	s_cselect_b64 vcc, -1, 0
	s_cmp_lg_u32 s12, 3
	v_cndmask_b32_e32 v0, v36, v0, vcc
	s_cselect_b64 vcc, -1, 0
	s_lshl_b32 s14, s2, 2
	s_and_b32 s14, s14, 0xfc
	s_add_i32 s14, s14, 0
	s_add_i32 s14, s14, 0x25a00
	v_cndmask_b32_e32 v2, v37, v0, vcc
	v_mov_b32_e32 v0, s14
	ds_read_b32 v3, v0
	s_and_b32 s15, s5, 0xffffc000
	s_lshl_b32 s16, s13, 6
	s_or_b32 s15, s16, s15
	v_mbcnt_lo_u32_b32 v4, -1, 0
	v_mbcnt_hi_u32_b32 v4, -1, v4
	s_lshl_b32 s2, s12, 8
	v_and_b32_e32 v14, 63, v4
	v_bitop3_b32 v0, v4, 63, v4 bitop3:0xc
	v_or_b32_e32 v1, s15, v14
	v_cvt_f32_ubyte0_e32 v6, v0
	v_mad_i64_i32 v[0:1], s[14:15], v1, s7, v[32:33]
	v_lshl_add_u64 v[8:9], v[0:1], 0, s[2:3]
	s_waitcnt lgkmcnt(0)
	v_readfirstlane_b32 s2, v3
	v_mul_f32_e32 v2, v2, v6
	v_and_b32_e32 v5, 31, v4
	v_lshl_add_u32 v0, s2, 6, v4
	v_ashrrev_i32_e32 v1, 3, v0
	v_exp_f32_e32 v17, v2
	v_add_u32_e32 v2, 0x200, v0
	v_readfirstlane_b32 s2, v0
	v_and_b32_e32 v0, -8, v1
	v_bfe_u32 v58, v4, 5, 1
	v_ashrrev_i32_e32 v2, 3, v2
	s_ashr_i32 s14, s2, 7
	v_and_or_b32 v59, s2, 64, v5
	v_ashrrev_i32_e32 v1, 31, v0
	v_add_u32_e32 v15, 0x48, v14
	v_lshlrev_b32_e32 v16, 4, v58
	v_mul_lo_u32 v3, v0, s8
	v_and_b32_e32 v10, -8, v2
	v_lshl_or_b32 v2, s14, 5, v5
	v_mul_u32_u24_e32 v4, 0x90, v59
	v_lshl_add_u64 v[12:13], v[0:1], 1, v[8:9]
	v_or_b32_e32 v18, v3, v14
	v_add_u32_e32 v19, v3, v15
	v_mul_lo_u32 v21, v2, s9
	v_add3_u32 v54, 0, v4, v16
	global_load_dwordx4 v[0:3], v[12:13], off offset:1856
	global_load_dwordx4 v[4:7], v[12:13], off offset:2880
	v_ashrrev_i32_e32 v11, 31, v10
	v_mul_lo_u32 v20, v10, s8
	v_lshl_add_u32 v12, v18, 1, 0
	v_lshl_add_u64 v[8:9], v[10:11], 1, v[8:9]
	global_load_dwordx4 v[60:63], v[8:9], off offset:1856
	global_load_dwordx4 v[64:67], v[8:9], off offset:2880
	v_or_b32_e32 v10, v20, v14
	v_add_u32_e32 v11, v20, v15
	v_add3_u32 v50, 0, v21, v16
	v_lshl_add_u32 v13, v19, 1, 0
	v_lshl_add_u32 v10, v10, 1, 0
	v_lshl_add_u32 v11, v11, 1, 0
	s_and_b32 s2, s11, 0xfffffc00
	s_lshl_b32 s13, s13, 2
	s_or_b32 s2, s13, s2
	s_or_b32 s12, s2, s12
	s_ashr_i32 s13, s12, 31
	s_lshl_b64 s[12:13], s[12:13], 15
	s_add_u32 s12, s1, s12
	s_addc_u32 s13, s4, s13
	s_lshl_b32 s2, s14, 12
	s_add_i32 s11, s11, s68
	s_add_i32 s5, s5, s6
	s_cmpk_gt_i32 s11, 0x7ff
	s_waitcnt vmcnt(2) lgkmcnt(0)
	ds_write_b16 v12, v4 offset:18432
	ds_write_b16_d16_hi v12, v4 offset:18576
	v_lshlrev_b32_e32 v14, 16, v0
	v_and_b32_e32 v0, 0xffff0000, v0
	v_lshlrev_b32_e32 v4, 16, v1
	v_and_b32_e32 v1, 0xffff0000, v1
	v_lshlrev_b32_e32 v15, 16, v2
	v_and_b32_e32 v2, 0xffff0000, v2
	v_lshlrev_b32_e32 v16, 16, v3
	v_and_b32_e32 v3, 0xffff0000, v3
	v_mul_f32_e32 v14, v17, v14
	v_mul_f32_e32 v0, v17, v0
	v_mul_f32_e32 v4, v17, v4
	v_mul_f32_e32 v1, v17, v1
	v_mul_f32_e32 v15, v17, v15
	v_mul_f32_e32 v2, v17, v2
	v_mul_f32_e32 v16, v17, v16
	v_mul_f32_e32 v3, v17, v3
	v_cvt_pk_bf16_f32 v14, v14, s0
	v_cvt_pk_bf16_f32 v0, v0, s0
	v_cvt_pk_bf16_f32 v4, v4, s0
	v_cvt_pk_bf16_f32 v1, v1, s0
	v_cvt_pk_bf16_f32 v15, v15, s0
	v_cvt_pk_bf16_f32 v2, v2, s0
	v_cvt_pk_bf16_f32 v16, v16, s0
	v_cvt_pk_bf16_f32 v3, v3, s0
	ds_write_b16 v12, v14
	ds_write_b16 v12, v0 offset:144
	ds_write_b16 v12, v4 offset:288
	ds_write_b16 v13, v1 offset:288
	ds_write_b16 v12, v5 offset:18720
	ds_write_b16_d16_hi v13, v5 offset:18720
	ds_write_b16 v12, v15 offset:576
	ds_write_b16 v13, v2 offset:576
	ds_write_b16 v12, v6 offset:19008
	ds_write_b16_d16_hi v13, v6 offset:19008
	ds_write_b16 v12, v16 offset:864
	ds_write_b16 v13, v3 offset:864
	ds_write_b16 v12, v7 offset:19296
	ds_write_b16_d16_hi v13, v7 offset:19296
	s_waitcnt vmcnt(0) lgkmcnt(0)
	v_mov_b64_e32 v[0:1], v[60:61]
	v_mov_b64_e32 v[2:3], v[62:63]
	v_mov_b64_e32 v[4:5], v[64:65]
	v_mov_b64_e32 v[6:7], v[66:67]
	ds_write_b16 v10, v4 offset:18432
	ds_write_b16_d16_hi v10, v4 offset:18576
	v_lshlrev_b32_e32 v8, 16, v0
	v_and_b32_e32 v0, 0xffff0000, v0
	v_lshlrev_b32_e32 v4, 16, v1
	v_and_b32_e32 v1, 0xffff0000, v1
	v_lshlrev_b32_e32 v9, 16, v2
	v_and_b32_e32 v2, 0xffff0000, v2
	v_lshlrev_b32_e32 v12, 16, v3
	v_and_b32_e32 v3, 0xffff0000, v3
	v_mul_f32_e32 v8, v17, v8
	v_mul_f32_e32 v0, v17, v0
	v_mul_f32_e32 v1, v17, v1
	v_mul_f32_e32 v2, v17, v2
	v_mul_f32_e32 v3, v17, v3
	v_mul_f32_e32 v4, v17, v4
	v_mul_f32_e32 v9, v17, v9
	v_mul_f32_e32 v12, v17, v12
	v_cvt_pk_bf16_f32 v8, v8, s0
	v_cvt_pk_bf16_f32 v0, v0, s0
	v_cvt_pk_bf16_f32 v1, v1, s0
	v_cvt_pk_bf16_f32 v2, v2, s0
	v_cvt_pk_bf16_f32 v3, v3, s0
	v_cvt_pk_bf16_f32 v4, v4, s0
	v_cvt_pk_bf16_f32 v9, v9, s0
	v_cvt_pk_bf16_f32 v12, v12, s0
	ds_write_b16 v10, v8
	ds_write_b16 v10, v0 offset:144
	ds_write_b16 v10, v4 offset:288
	ds_write_b16 v11, v1 offset:288
	ds_write_b16 v10, v5 offset:18720
	ds_write_b16_d16_hi v11, v5 offset:18720
	ds_write_b16 v10, v9 offset:576
	ds_write_b16 v11, v2 offset:576
	ds_write_b16 v10, v6 offset:19008
	ds_write_b16_d16_hi v11, v6 offset:19008
	ds_write_b16 v10, v12 offset:864
	ds_write_b16 v11, v3 offset:864
	ds_write_b16 v10, v7 offset:19296
	ds_write_b16_d16_hi v11, v7 offset:19296
	s_waitcnt lgkmcnt(0)
	s_barrier
; #define LAS __attribute__((address_space(3)))
; __device__ __forceinline__ bf16 f2bf(float f) { return (bf16)(pk2(f, 0.f) & 0xffffu); }
; __device__ __forceinline__ int crow(int r, int hi) { return (r & 3) + 8 * (r >> 2) + 4 * hi; }
; #define MFMA32(a, b, c) __builtin_amdgcn_mfma_f32_32x32x16_bf16((a), (b), (c), 0, 0, 0)
; __device__ __forceinline__ void ret_kv_item(LAS unsigned char* lds, const bf16* Z, bf16* AT, int b, int c, int hh, float lg) {
;     ...
;     const int eb = wid >> 1, db0 = 2 * (wid & 1);
;     f32x16 a0, a1;
; #pragma unroll
;     for (int r = 0; r < 16; ++r) { a0[r] = 0.f; a1[r] = 0.f; }
; #pragma unroll
;     for (int ks = 0; ks < 4; ++ks) {
;         const bf16x8 af = *(const LAS bf16x8*)(VTt + (32 * eb + r32) * 72 + 16 * ks + 8 * hi);
;         const bf16x8 b0 = *(const LAS bf16x8*)(KT + (32 * db0 + r32) * 72 + 16 * ks + 8 * hi), b1 = *(const LAS bf16x8*)(KT + (32 * db0 + 32 + r32) * 72 + 16 * ks + 8 * hi);
;         a0 = MFMA32(af, b0, a0); a1 = MFMA32(af, b1, a1);
;     }
;     bf16* o = AT + (size_t)((b * 256 + c) * 4 + hh) * 16384;
; #pragma unroll
;     for (int r = 0; r < 16; ++r) { const int e = 32 * eb + crow(r, hi); o[e * 128 + 32 * db0 + r32] = f2bf(a0[r]); o[e * 128 + 32 * db0 + 32 + r32] = f2bf(a1[r]); }
;     __syncthreads();
	ds_read_b128 v[16:19], v50 offset:18432
	ds_read_b128 v[0:3], v54
	ds_read_b128 v[38:41], v50 offset:18464
	ds_read_b128 v[42:45], v54 offset:32
	s_waitcnt lgkmcnt(2)
	v_mfma_f32_32x32x16_bf16 v[0:15], v[16:19], v[0:3], 0
	ds_read_b128 v[20:23], v54 offset:4608
	ds_read_b128 v[46:49], v54 offset:4640
	s_waitcnt lgkmcnt(1)
	v_mfma_f32_32x32x16_bf16 v[16:31], v[16:19], v[20:23], 0
	v_mfma_f32_32x32x16_bf16 v[0:15], v[38:41], v[42:45], v[0:15]
	s_waitcnt lgkmcnt(0)
	v_mfma_f32_32x32x16_bf16 v[16:31], v[38:41], v[46:49], v[16:31]
	ds_read_b128 v[38:41], v50 offset:18496
	ds_read_b128 v[42:45], v54 offset:64
	ds_read_b128 v[46:49], v50 offset:18528
	ds_read_b128 v[50:53], v54 offset:96
	s_waitcnt lgkmcnt(2)
	v_mfma_f32_32x32x16_bf16 v[0:15], v[38:41], v[42:45], v[0:15]
	ds_read_b128 v[42:45], v54 offset:4672
	ds_read_b128 v[54:57], v54 offset:4704
	s_waitcnt lgkmcnt(1)
	v_mfma_f32_32x32x16_bf16 v[16:31], v[38:41], v[42:45], v[16:31]
	v_lshlrev_b32_e32 v38, 9, v58
	v_or3_b32 v38, s2, v38, v59
	v_ashrrev_i32_e32 v39, 31, v38
	v_lshl_add_u64 v[38:39], v[38:39], 1, s[12:13]
	v_add_co_u32_e32 v40, vcc, s10, v38
	v_mfma_f32_32x32x16_bf16 v[0:15], v[46:49], v[50:53], v[0:15]
	s_nop 0
	v_addc_co_u32_e32 v41, vcc, 0, v39, vcc
	s_waitcnt lgkmcnt(0)
	v_mfma_f32_32x32x16_bf16 v[16:31], v[46:49], v[54:57], v[16:31]
	s_nop 7
	v_cvt_pk_bf16_f32 v0, v0, s0
	v_cvt_pk_bf16_f32 v1, v1, s0
	v_cvt_pk_bf16_f32 v2, v2, s0
	v_cvt_pk_bf16_f32 v3, v3, s0
	v_cvt_pk_bf16_f32 v4, v4, s0
	v_cvt_pk_bf16_f32 v5, v5, s0
	v_cvt_pk_bf16_f32 v6, v6, s0
	v_cvt_pk_bf16_f32 v16, v16, s0
	v_cvt_pk_bf16_f32 v17, v17, s0
	v_cvt_pk_bf16_f32 v18, v18, s0
	v_cvt_pk_bf16_f32 v19, v19, s0
	v_cvt_pk_bf16_f32 v20, v20, s0
	v_cvt_pk_bf16_f32 v21, v21, s0
	v_cvt_pk_bf16_f32 v22, v22, s0
	v_cvt_pk_bf16_f32 v7, v7, s0
	v_cvt_pk_bf16_f32 v23, v23, s0
	v_cvt_pk_bf16_f32 v8, v8, s0
	v_cvt_pk_bf16_f32 v24, v24, s0
	v_cvt_pk_bf16_f32 v9, v9, s0
	v_cvt_pk_bf16_f32 v25, v25, s0
	v_cvt_pk_bf16_f32 v10, v10, s0
	v_cvt_pk_bf16_f32 v26, v26, s0
	v_cvt_pk_bf16_f32 v11, v11, s0
	v_cvt_pk_bf16_f32 v27, v27, s0
	v_cvt_pk_bf16_f32 v12, v12, s0
	v_cvt_pk_bf16_f32 v28, v28, s0
	v_cvt_pk_bf16_f32 v13, v13, s0
	v_cvt_pk_bf16_f32 v29, v29, s0
	v_cvt_pk_bf16_f32 v14, v14, s0
	v_cvt_pk_bf16_f32 v30, v30, s0
	v_cvt_pk_bf16_f32 v15, v15, s0
	v_cvt_pk_bf16_f32 v31, v31, s0
	global_store_short v[38:39], v0, off
	global_store_short v[38:39], v16, off offset:64
	global_store_short v[38:39], v1, off offset:256
	global_store_short v[38:39], v17, off offset:320
	global_store_short v[38:39], v2, off offset:512
	global_store_short v[38:39], v18, off offset:576
	global_store_short v[38:39], v3, off offset:768
	global_store_short v[38:39], v19, off offset:832
	global_store_short v[38:39], v4, off offset:2048
	global_store_short v[38:39], v20, off offset:2112
	global_store_short v[38:39], v5, off offset:2304
	global_store_short v[38:39], v21, off offset:2368
	global_store_short v[38:39], v6, off offset:2560
	global_store_short v[38:39], v22, off offset:2624
	global_store_short v[38:39], v7, off offset:2816
	global_store_short v[38:39], v23, off offset:2880
	global_store_short v[40:41], v8, off
	global_store_short v[40:41], v24, off offset:64
	global_store_short v[40:41], v9, off offset:256
	global_store_short v[40:41], v25, off offset:320
	global_store_short v[40:41], v10, off offset:512
	global_store_short v[40:41], v26, off offset:576
	global_store_short v[40:41], v11, off offset:768
	global_store_short v[40:41], v27, off offset:832
	global_store_short v[40:41], v12, off offset:2048
	global_store_short v[40:41], v28, off offset:2112
	global_store_short v[40:41], v13, off offset:2304
	global_store_short v[40:41], v29, off offset:2368
	global_store_short v[40:41], v14, off offset:2560
	global_store_short v[40:41], v30, off offset:2624
	global_store_short v[40:41], v15, off offset:2816
	global_store_short v[40:41], v31, off offset:2880
	s_waitcnt lgkmcnt(0)
	s_barrier
	s_cbranch_scc0 .LBB0_440

; #define LAS __attribute__((address_space(3)))
; __device__ __forceinline__ float bf2f(unsigned b) { return __uint_as_float(b << 16); }
; __device__ __forceinline__ bf16 f2bf(float f) { return (bf16)(pk2(f, 0.f) & 0xffffu); }
; __device__ __forceinline__ float ex2f(float x) { return __builtin_amdgcn_exp2f(x); }
; __device__ __forceinline__ void ret_scan(LAS unsigned char* lds, bf16* AT, float* out, int G, const float* lgs) {
;     const int t_ = my_tid(lds);
;     for (int idx = blockIdx.x * 512 + t_; idx < 2 * 4 * 128 * 128; idx += G * 512) {
;         const int d = idx & 127, e = (idx >> 7) & 127, hh = (idx >> 14) & 3, b = idx >> 16;
;         const float g64 = ex2f(64.f * lgs[hh]);
;         bf16* p = AT + (size_t)(b * 256 * 4 + hh) * 16384 + e * 128 + d; float S = 0.f;
;         for (int c = 0; c < 256; c += 8) { float a[8];
; #pragma unroll
;             for (int i = 0; i < 8; ++i) a[i] = bf2f(p[(size_t)(c + i) * 65536]);
; #pragma unroll
;             for (int i = 0; i < 8; ++i) { p[(size_t)(c + i) * 65536] = f2bf(S); S = g64 * S + a[i]; } }
.LBB0_503:
	v_bfe_u32 v11, v6, 14, 2
	v_cmp_eq_u32_e32 vcc, 1, v11
	v_ashrrev_i32_e32 v12, 16, v6
	v_lshlrev_b32_e32 v14, 1, v6
	v_cndmask_b32_e32 v4, v7, v8, vcc
	v_cmp_ne_u32_e32 vcc, 2, v11
	v_lshrrev_b32_e32 v0, 7, v6
	s_mov_b32 s18, -8
	v_cndmask_b32_e32 v4, v9, v4, vcc
	v_cmp_ne_u32_e32 vcc, 3, v11
	s_nop 1
	v_cndmask_b32_e32 v4, v10, v4, vcc
	v_mul_f32_e32 v4, 0x42800000, v4
	v_exp_f32_e32 v13, v4
	v_lshl_or_b32 v4, v12, 10, v11
	v_ashrrev_i32_e32 v5, 31, v4
	v_lshlrev_b64 v[4:5], 15, v[4:5]
	v_and_or_b32 v4, v14, s1, v4
	v_lshl_add_u64 v[4:5], v[2:3], 0, v[4:5]
	v_mov_b32_e32 v14, 0
	s_mov_b32 s98, 0x20000
	s_mov_b32 s99, 0
	s_mov_b32 s100, 0xffe20000
	s_mov_b32 s101, -1
	v_lshl_add_u64 v[62:63], v[4:5], 0, s[100:101]
	v_mov_b64_e32 v[64:65], v[62:63]
	global_load_ushort v66, v[64:65], off
	v_lshl_add_u64 v[64:65], v[64:65], 0, s[98:99]
	global_load_ushort v67, v[64:65], off
	v_lshl_add_u64 v[64:65], v[64:65], 0, s[98:99]
	global_load_ushort v68, v[64:65], off
	v_lshl_add_u64 v[64:65], v[64:65], 0, s[98:99]
	global_load_ushort v69, v[64:65], off
	v_lshl_add_u64 v[64:65], v[64:65], 0, s[98:99]
	global_load_ushort v70, v[64:65], off
	v_lshl_add_u64 v[64:65], v[64:65], 0, s[98:99]
	global_load_ushort v71, v[64:65], off
	v_lshl_add_u64 v[64:65], v[64:65], 0, s[98:99]
	global_load_ushort v72, v[64:65], off
	v_lshl_add_u64 v[64:65], v[64:65], 0, s[98:99]
	global_load_ushort v73, v[64:65], off
	v_lshl_add_u64 v[64:65], v[64:65], 0, s[98:99]
	global_load_ushort v74, v[64:65], off
	v_lshl_add_u64 v[64:65], v[64:65], 0, s[98:99]
	global_load_ushort v75, v[64:65], off
	v_lshl_add_u64 v[64:65], v[64:65], 0, s[98:99]
	global_load_ushort v76, v[64:65], off
	v_lshl_add_u64 v[64:65], v[64:65], 0, s[98:99]
	global_load_ushort v77, v[64:65], off
	v_lshl_add_u64 v[64:65], v[64:65], 0, s[98:99]
	global_load_ushort v78, v[64:65], off
	v_lshl_add_u64 v[64:65], v[64:65], 0, s[98:99]
	global_load_ushort v79, v[64:65], off
	v_lshl_add_u64 v[64:65], v[64:65], 0, s[98:99]
	global_load_ushort v80, v[64:65], off
	v_lshl_add_u64 v[64:65], v[64:65], 0, s[98:99]
	global_load_ushort v81, v[64:65], off
	v_lshl_add_u64 v[64:65], v[64:65], 0, s[98:99]
	global_load_ushort v82, v[64:65], off
	v_lshl_add_u64 v[64:65], v[64:65], 0, s[98:99]
	global_load_ushort v83, v[64:65], off
	v_lshl_add_u64 v[64:65], v[64:65], 0, s[98:99]
	global_load_ushort v84, v[64:65], off
	v_lshl_add_u64 v[64:65], v[64:65], 0, s[98:99]
	global_load_ushort v85, v[64:65], off
	v_lshl_add_u64 v[64:65], v[64:65], 0, s[98:99]
	global_load_ushort v86, v[64:65], off
	v_lshl_add_u64 v[64:65], v[64:65], 0, s[98:99]
	global_load_ushort v87, v[64:65], off
	v_lshl_add_u64 v[64:65], v[64:65], 0, s[98:99]
	global_load_ushort v88, v[64:65], off
	v_lshl_add_u64 v[64:65], v[64:65], 0, s[98:99]
	global_load_ushort v89, v[64:65], off
	v_lshl_add_u64 v[64:65], v[64:65], 0, s[98:99]
	global_load_ushort v90, v[64:65], off
	v_lshl_add_u64 v[64:65], v[64:65], 0, s[98:99]
	global_load_ushort v91, v[64:65], off
	v_lshl_add_u64 v[64:65], v[64:65], 0, s[98:99]
	global_load_ushort v92, v[64:65], off
	v_lshl_add_u64 v[64:65], v[64:65], 0, s[98:99]
	global_load_ushort v93, v[64:65], off
	v_lshl_add_u64 v[64:65], v[64:65], 0, s[98:99]
	global_load_ushort v94, v[64:65], off
	v_lshl_add_u64 v[64:65], v[64:65], 0, s[98:99]
	global_load_ushort v95, v[64:65], off
	v_lshl_add_u64 v[64:65], v[64:65], 0, s[98:99]
	global_load_ushort v96, v[64:65], off
	v_lshl_add_u64 v[64:65], v[64:65], 0, s[98:99]
	global_load_ushort v97, v[64:65], off
	v_lshl_add_u64 v[64:65], v[64:65], 0, s[98:99]
	s_mov_b32 s18, 0
	s_waitcnt vmcnt(16)
.Lrs_loop:
	s_waitcnt vmcnt(32)
	v_lshlrev_b32_e32 v98, 16, v66
	v_lshlrev_b32_e32 v99, 16, v67
	v_lshlrev_b32_e32 v100, 16, v68
	v_lshlrev_b32_e32 v101, 16, v69
	v_lshlrev_b32_e32 v102, 16, v70
	v_lshlrev_b32_e32 v103, 16, v71
	v_lshlrev_b32_e32 v104, 16, v72
	v_lshlrev_b32_e32 v105, 16, v73
	v_lshlrev_b32_e32 v106, 16, v74
	v_lshlrev_b32_e32 v107, 16, v75
	v_lshlrev_b32_e32 v108, 16, v76
	v_lshlrev_b32_e32 v109, 16, v77
	v_lshlrev_b32_e32 v110, 16, v78
	v_lshlrev_b32_e32 v111, 16, v79
	v_lshlrev_b32_e32 v112, 16, v80
	v_lshlrev_b32_e32 v113, 16, v81
	s_cmp_ge_u32 s18, 7
	s_cbranch_scc1 .Lrs_nl0
	global_load_ushort v66, v[64:65], off
	v_lshl_add_u64 v[64:65], v[64:65], 0, s[98:99]
	global_load_ushort v67, v[64:65], off
	v_lshl_add_u64 v[64:65], v[64:65], 0, s[98:99]
	global_load_ushort v68, v[64:65], off
	v_lshl_add_u64 v[64:65], v[64:65], 0, s[98:99]
	global_load_ushort v69, v[64:65], off
	v_lshl_add_u64 v[64:65], v[64:65], 0, s[98:99]
	global_load_ushort v70, v[64:65], off
	v_lshl_add_u64 v[64:65], v[64:65], 0, s[98:99]
	global_load_ushort v71, v[64:65], off
	v_lshl_add_u64 v[64:65], v[64:65], 0, s[98:99]
	global_load_ushort v72, v[64:65], off
	v_lshl_add_u64 v[64:65], v[64:65], 0, s[98:99]
	global_load_ushort v73, v[64:65], off
	v_lshl_add_u64 v[64:65], v[64:65], 0, s[98:99]
	global_load_ushort v74, v[64:65], off
	v_lshl_add_u64 v[64:65], v[64:65], 0, s[98:99]
	global_load_ushort v75, v[64:65], off
	v_lshl_add_u64 v[64:65], v[64:65], 0, s[98:99]
	global_load_ushort v76, v[64:65], off
	v_lshl_add_u64 v[64:65], v[64:65], 0, s[98:99]
	global_load_ushort v77, v[64:65], off
	v_lshl_add_u64 v[64:65], v[64:65], 0, s[98:99]
	global_load_ushort v78, v[64:65], off
	v_lshl_add_u64 v[64:65], v[64:65], 0, s[98:99]
	global_load_ushort v79, v[64:65], off
	v_lshl_add_u64 v[64:65], v[64:65], 0, s[98:99]
	global_load_ushort v80, v[64:65], off
	v_lshl_add_u64 v[64:65], v[64:65], 0, s[98:99]
	global_load_ushort v81, v[64:65], off
	v_lshl_add_u64 v[64:65], v[64:65], 0, s[98:99]
; __device__ __forceinline__ float bf2f(unsigned b) { return __uint_as_float(b << 16); }
; __device__ __forceinline__ bf16 f2bf(float f) { return (bf16)(pk2(f, 0.f) & 0xffffu); }
; __device__ __forceinline__ void ret_scan(LAS unsigned char* lds, bf16* AT, float* out, int G, const float* lgs) {
;     ...
;         for (int c = 0; c < 256; c += 8) { float a[8];
; #pragma unroll
;             for (int i = 0; i < 8; ++i) a[i] = bf2f(p[(size_t)(c + i) * 65536]);
; #pragma unroll
;             for (int i = 0; i < 8; ++i) { p[(size_t)(c + i) * 65536] = f2bf(S); S = g64 * S + a[i]; } }
.Lrs_nl0:
	v_cvt_pk_bf16_f32 v114, v14, v14
	global_store_short v[62:63], v114, off
	v_fmac_f32_e32 v98, v13, v14
	v_lshl_add_u64 v[62:63], v[62:63], 0, s[98:99]
	v_cvt_pk_bf16_f32 v114, v98, v98
	global_store_short v[62:63], v114, off
	v_fmac_f32_e32 v99, v13, v98
	v_lshl_add_u64 v[62:63], v[62:63], 0, s[98:99]
	v_cvt_pk_bf16_f32 v114, v99, v99
	global_store_short v[62:63], v114, off
	v_fmac_f32_e32 v100, v13, v99
	v_lshl_add_u64 v[62:63], v[62:63], 0, s[98:99]
	v_cvt_pk_bf16_f32 v114, v100, v100
	global_store_short v[62:63], v114, off
	v_fmac_f32_e32 v101, v13, v100
	v_lshl_add_u64 v[62:63], v[62:63], 0, s[98:99]
	v_cvt_pk_bf16_f32 v114, v101, v101
	global_store_short v[62:63], v114, off
	v_fmac_f32_e32 v102, v13, v101
	v_lshl_add_u64 v[62:63], v[62:63], 0, s[98:99]
	v_cvt_pk_bf16_f32 v114, v102, v102
	global_store_short v[62:63], v114, off
	v_fmac_f32_e32 v103, v13, v102
	v_lshl_add_u64 v[62:63], v[62:63], 0, s[98:99]
	v_cvt_pk_bf16_f32 v114, v103, v103
	global_store_short v[62:63], v114, off
	v_fmac_f32_e32 v104, v13, v103
	v_lshl_add_u64 v[62:63], v[62:63], 0, s[98:99]
	v_cvt_pk_bf16_f32 v114, v104, v104
	global_store_short v[62:63], v114, off
	v_fmac_f32_e32 v105, v13, v104
	v_lshl_add_u64 v[62:63], v[62:63], 0, s[98:99]
	v_cvt_pk_bf16_f32 v114, v105, v105
	global_store_short v[62:63], v114, off
	v_fmac_f32_e32 v106, v13, v105
	v_lshl_add_u64 v[62:63], v[62:63], 0, s[98:99]
	v_cvt_pk_bf16_f32 v114, v106, v106
	global_store_short v[62:63], v114, off
	v_fmac_f32_e32 v107, v13, v106
	v_lshl_add_u64 v[62:63], v[62:63], 0, s[98:99]
	v_cvt_pk_bf16_f32 v114, v107, v107
	global_store_short v[62:63], v114, off
	v_fmac_f32_e32 v108, v13, v107
	v_lshl_add_u64 v[62:63], v[62:63], 0, s[98:99]
	v_cvt_pk_bf16_f32 v114, v108, v108
	global_store_short v[62:63], v114, off
	v_fmac_f32_e32 v109, v13, v108
	v_lshl_add_u64 v[62:63], v[62:63], 0, s[98:99]
	v_cvt_pk_bf16_f32 v114, v109, v109
	global_store_short v[62:63], v114, off
	v_fmac_f32_e32 v110, v13, v109
	v_lshl_add_u64 v[62:63], v[62:63], 0, s[98:99]
	v_cvt_pk_bf16_f32 v114, v110, v110
	global_store_short v[62:63], v114, off
	v_fmac_f32_e32 v111, v13, v110
	v_lshl_add_u64 v[62:63], v[62:63], 0, s[98:99]
	v_cvt_pk_bf16_f32 v114, v111, v111
	global_store_short v[62:63], v114, off
	v_fmac_f32_e32 v112, v13, v111
	v_lshl_add_u64 v[62:63], v[62:63], 0, s[98:99]
	v_cvt_pk_bf16_f32 v114, v112, v112
	global_store_short v[62:63], v114, off
	v_fmac_f32_e32 v113, v13, v112
	v_lshl_add_u64 v[62:63], v[62:63], 0, s[98:99]
	v_mov_b32_e32 v14, v113
	s_waitcnt vmcnt(32)
	v_lshlrev_b32_e32 v98, 16, v82
	v_lshlrev_b32_e32 v99, 16, v83
	v_lshlrev_b32_e32 v100, 16, v84
	v_lshlrev_b32_e32 v101, 16, v85
	v_lshlrev_b32_e32 v102, 16, v86
	v_lshlrev_b32_e32 v103, 16, v87
	v_lshlrev_b32_e32 v104, 16, v88
	v_lshlrev_b32_e32 v105, 16, v89
	v_lshlrev_b32_e32 v106, 16, v90
	v_lshlrev_b32_e32 v107, 16, v91
	v_lshlrev_b32_e32 v108, 16, v92
	v_lshlrev_b32_e32 v109, 16, v93
	v_lshlrev_b32_e32 v110, 16, v94
	v_lshlrev_b32_e32 v111, 16, v95
	v_lshlrev_b32_e32 v112, 16, v96
	v_lshlrev_b32_e32 v113, 16, v97
	s_cmp_ge_u32 s18, 7
	s_cbranch_scc1 .Lrs_nl1
	global_load_ushort v82, v[64:65], off
	v_lshl_add_u64 v[64:65], v[64:65], 0, s[98:99]
	global_load_ushort v83, v[64:65], off
	v_lshl_add_u64 v[64:65], v[64:65], 0, s[98:99]
	global_load_ushort v84, v[64:65], off
	v_lshl_add_u64 v[64:65], v[64:65], 0, s[98:99]
	global_load_ushort v85, v[64:65], off
	v_lshl_add_u64 v[64:65], v[64:65], 0, s[98:99]
	global_load_ushort v86, v[64:65], off
	v_lshl_add_u64 v[64:65], v[64:65], 0, s[98:99]
	global_load_ushort v87, v[64:65], off
	v_lshl_add_u64 v[64:65], v[64:65], 0, s[98:99]
	global_load_ushort v88, v[64:65], off
	v_lshl_add_u64 v[64:65], v[64:65], 0, s[98:99]
	global_load_ushort v89, v[64:65], off
	v_lshl_add_u64 v[64:65], v[64:65], 0, s[98:99]
	global_load_ushort v90, v[64:65], off
	v_lshl_add_u64 v[64:65], v[64:65], 0, s[98:99]
	global_load_ushort v91, v[64:65], off
	v_lshl_add_u64 v[64:65], v[64:65], 0, s[98:99]
	global_load_ushort v92, v[64:65], off
	v_lshl_add_u64 v[64:65], v[64:65], 0, s[98:99]
	global_load_ushort v93, v[64:65], off
	v_lshl_add_u64 v[64:65], v[64:65], 0, s[98:99]
	global_load_ushort v94, v[64:65], off
	v_lshl_add_u64 v[64:65], v[64:65], 0, s[98:99]
	global_load_ushort v95, v[64:65], off
	v_lshl_add_u64 v[64:65], v[64:65], 0, s[98:99]
	global_load_ushort v96, v[64:65], off
	v_lshl_add_u64 v[64:65], v[64:65], 0, s[98:99]
	global_load_ushort v97, v[64:65], off
	v_lshl_add_u64 v[64:65], v[64:65], 0, s[98:99]
; __device__ __forceinline__ float bf2f(unsigned b) { return __uint_as_float(b << 16); }
; __device__ __forceinline__ bf16 f2bf(float f) { return (bf16)(pk2(f, 0.f) & 0xffffu); }
; __device__ __forceinline__ void ret_scan(LAS unsigned char* lds, bf16* AT, float* out, int G, const float* lgs) {
;     ...
;         for (int c = 0; c < 256; c += 8) { float a[8];
; #pragma unroll
;             for (int i = 0; i < 8; ++i) a[i] = bf2f(p[(size_t)(c + i) * 65536]);
; #pragma unroll
;             for (int i = 0; i < 8; ++i) { p[(size_t)(c + i) * 65536] = f2bf(S); S = g64 * S + a[i]; } }
;         out[O_PRET + (size_t)((b * 4 + hh) * 128 + d) * 128 + e] = S;
.Lrs_nl1:
	v_cvt_pk_bf16_f32 v114, v14, v14
	global_store_short v[62:63], v114, off
	v_fmac_f32_e32 v98, v13, v14
	v_lshl_add_u64 v[62:63], v[62:63], 0, s[98:99]
	v_cvt_pk_bf16_f32 v114, v98, v98
	global_store_short v[62:63], v114, off
	v_fmac_f32_e32 v99, v13, v98
	v_lshl_add_u64 v[62:63], v[62:63], 0, s[98:99]
	v_cvt_pk_bf16_f32 v114, v99, v99
	global_store_short v[62:63], v114, off
	v_fmac_f32_e32 v100, v13, v99
	v_lshl_add_u64 v[62:63], v[62:63], 0, s[98:99]
	v_cvt_pk_bf16_f32 v114, v100, v100
	global_store_short v[62:63], v114, off
	v_fmac_f32_e32 v101, v13, v100
	v_lshl_add_u64 v[62:63], v[62:63], 0, s[98:99]
	v_cvt_pk_bf16_f32 v114, v101, v101
	global_store_short v[62:63], v114, off
	v_fmac_f32_e32 v102, v13, v101
	v_lshl_add_u64 v[62:63], v[62:63], 0, s[98:99]
	v_cvt_pk_bf16_f32 v114, v102, v102
	global_store_short v[62:63], v114, off
	v_fmac_f32_e32 v103, v13, v102
	v_lshl_add_u64 v[62:63], v[62:63], 0, s[98:99]
	v_cvt_pk_bf16_f32 v114, v103, v103
	global_store_short v[62:63], v114, off
	v_fmac_f32_e32 v104, v13, v103
	v_lshl_add_u64 v[62:63], v[62:63], 0, s[98:99]
	v_cvt_pk_bf16_f32 v114, v104, v104
	global_store_short v[62:63], v114, off
	v_fmac_f32_e32 v105, v13, v104
	v_lshl_add_u64 v[62:63], v[62:63], 0, s[98:99]
	v_cvt_pk_bf16_f32 v114, v105, v105
	global_store_short v[62:63], v114, off
	v_fmac_f32_e32 v106, v13, v105
	v_lshl_add_u64 v[62:63], v[62:63], 0, s[98:99]
	v_cvt_pk_bf16_f32 v114, v106, v106
	global_store_short v[62:63], v114, off
	v_fmac_f32_e32 v107, v13, v106
	v_lshl_add_u64 v[62:63], v[62:63], 0, s[98:99]
	v_cvt_pk_bf16_f32 v114, v107, v107
	global_store_short v[62:63], v114, off
	v_fmac_f32_e32 v108, v13, v107
	v_lshl_add_u64 v[62:63], v[62:63], 0, s[98:99]
	v_cvt_pk_bf16_f32 v114, v108, v108
	global_store_short v[62:63], v114, off
	v_fmac_f32_e32 v109, v13, v108
	v_lshl_add_u64 v[62:63], v[62:63], 0, s[98:99]
	v_cvt_pk_bf16_f32 v114, v109, v109
	global_store_short v[62:63], v114, off
	v_fmac_f32_e32 v110, v13, v109
	v_lshl_add_u64 v[62:63], v[62:63], 0, s[98:99]
	v_cvt_pk_bf16_f32 v114, v110, v110
	global_store_short v[62:63], v114, off
	v_fmac_f32_e32 v111, v13, v110
	v_lshl_add_u64 v[62:63], v[62:63], 0, s[98:99]
	v_cvt_pk_bf16_f32 v114, v111, v111
	global_store_short v[62:63], v114, off
	v_fmac_f32_e32 v112, v13, v111
	v_lshl_add_u64 v[62:63], v[62:63], 0, s[98:99]
	v_cvt_pk_bf16_f32 v114, v112, v112
	global_store_short v[62:63], v114, off
	v_fmac_f32_e32 v113, v13, v112
	v_lshl_add_u64 v[62:63], v[62:63], 0, s[98:99]
	v_mov_b32_e32 v14, v113
	s_add_i32 s18, s18, 1
	s_cmp_lt_u32 s18, 8
	s_cbranch_scc1 .Lrs_loop
	v_and_b32_e32 v4, 0x7f, v6
	v_lshlrev_b32_e32 v5, 9, v12
	v_lshlrev_b32_e32 v11, 7, v11
	v_or3_b32 v4, v11, v5, v4
	v_ashrrev_i32_e32 v5, 31, v4
	v_and_b32_e32 v0, 0x7f, v0
	v_lshlrev_b64 v[4:5], 9, v[4:5]
	v_lshl_add_u64 v[4:5], s[2:3], 0, v[4:5]
	v_lshlrev_b32_e32 v0, 2, v0
	v_lshl_add_u64 v[4:5], v[4:5], 0, v[0:1]
	v_add_co_u32_e32 v4, vcc, 0x9600000, v4
	v_add_u32_e32 v6, s0, v6
	s_nop 0
	v_addc_co_u32_e32 v5, vcc, 0, v5, vcc
	v_cmp_lt_i32_e32 vcc, s17, v6
	s_or_b64 s[6:7], vcc, s[6:7]
	global_store_dword v[4:5], v14, off
	s_andn2_b64 exec, exec, s[6:7]
	s_cbranch_execnz .LBB0_503
